# layer-1 w_in GEMM 3-way split with the tile enumeration kept XCD-contiguous (198 decode positions per XCD) so that workgroups of an XCD still share A and B tiles
# speedup vs baseline: 1.0103x; 1.0103x over previous
.Lgi_sk_rm:
	s_and_b32 s0, s57, 7
	s_lshr_b32 s1, s57, 3
	s_mul_i32 s0, s0, 198
	s_add_u32 s57, s0, s1
	s_mul_i32 s0, s57, 0x5051
	s_lshr_b32 s0, s0, 22
	s_mul_i32 s1, s0, 204
	s_sub_u32 s1, s57, s1
	s_lshl_b32 s1, s1, 3
	s_add_u32 s57, s1, s0
